# PH4 ping-pong variant: pure-MFMA phase (PV of previous tile + QK) and pure-VALU phase per wave, wave groups in opposite phases
# baseline (speedup 1.0000x reference)
; template <bool MASK>
; DI void attn_unit(LAS unsigned char* lds, const bf16_t* qrow, const bf16_t* kbase, int kpitch, const bf16_t* vtbase, int vtpitch, int ntiles,
;                   const unsigned long long* maskp, bf16_t* orow, float c1, float c2) {
;     ...
;     unsigned long long mw_next = ~0ull;
;     if (MASK) mw_next = maskp[0];
;     __syncthreads();
;     for (int kt = 0; kt < ntiles; ++kt) {
;         const bool more = kt + 1 < ntiles;
;         if (more) {
;             const size_t ko = (size_t)(kt + 1) * 64 * kpitch; const int vo = (kt + 1) * 64;
;             pk[0] = *(const u32x4*)(kg0 + ko); pk[1] = *(const u32x4*)(kg1 + ko); pv[0] = *(const u32x4*)(vg0 + vo); pv[1] = *(const u32x4*)(vg1 + vo);
;         }
;         const unsigned long long mw = mw_next;
;         if (MASK && more) mw_next = maskp[(size_t)(kt + 1) * S_];
.LBB0_1243:
	v_mov_b32_e32 v63, 0
	s_andn2_b64 vcc, exec, s[2:3]
	v_mov_b32_e32 v62, v63
	v_mov_b32_e32 v61, v63
	v_mov_b32_e32 v60, v63
	v_mov_b32_e32 v59, v63
	v_mov_b32_e32 v58, v63
	v_mov_b32_e32 v57, v63
	v_mov_b32_e32 v56, v63
	v_mov_b32_e32 v55, v63
	v_mov_b32_e32 v54, v63
	v_mov_b32_e32 v53, v63
	v_mov_b32_e32 v52, v63
	v_mov_b32_e32 v51, v63
	v_mov_b32_e32 v50, v63
	v_mov_b32_e32 v49, v63
	v_mov_b32_e32 v48, v63
	v_mov_b32_e32 v47, v63
	v_mov_b32_e32 v46, v63
	v_mov_b32_e32 v45, v63
	v_mov_b32_e32 v44, v63
	v_mov_b32_e32 v43, v63
	v_mov_b32_e32 v42, v63
	v_mov_b32_e32 v41, v63
	v_mov_b32_e32 v40, v63
	v_mov_b32_e32 v39, v63
	v_mov_b32_e32 v38, v63
	v_mov_b32_e32 v37, v63
	v_mov_b32_e32 v36, v63
	v_mov_b32_e32 v35, v63
	v_mov_b32_e32 v34, v63
	v_mov_b32_e32 v33, v63
	v_mov_b32_e32 v32, v63
	v_mov_b32_e32 v31, v63
	v_mov_b32_e32 v30, v63
	v_mov_b32_e32 v29, v63
	v_mov_b32_e32 v28, v63
	v_mov_b32_e32 v27, v63
	v_mov_b32_e32 v26, v63
	v_mov_b32_e32 v25, v63
	v_mov_b32_e32 v24, v63
	v_mov_b32_e32 v23, v63
	v_mov_b32_e32 v22, v63
	v_mov_b32_e32 v21, v63
	v_mov_b32_e32 v20, v63
	v_mov_b32_e32 v19, v63
	v_mov_b32_e32 v18, v63
	v_mov_b32_e32 v17, v63
	v_mov_b32_e32 v16, v63
	v_mov_b32_e32 v15, v63
	v_mov_b32_e32 v14, v63
	v_mov_b32_e32 v13, v63
	v_mov_b32_e32 v12, v63
	v_mov_b32_e32 v11, v63
	v_mov_b32_e32 v10, v63
	v_mov_b32_e32 v9, v63
	v_mov_b32_e32 v8, v63
	v_mov_b32_e32 v7, v63
	v_mov_b32_e32 v6, v63
	v_mov_b32_e32 v5, v63
	v_mov_b32_e32 v4, v63
	v_mov_b32_e32 v3, v63
	v_mov_b32_e32 v2, v63
	v_mov_b32_e32 v1, v63
	v_mov_b32_e32 v0, v63
	v_mov_b32_e32 v149, v63
	s_mov_b64 s[30:31], 0x8000
	s_cbranch_vccnz .LBB0_1238
	s_add_i32 s17, s16, 1
	s_add_u32 s2, s18, s22
	s_addc_u32 s3, 0, 0
	s_add_u32 s2, s2, 0x20908000
	v_and_b32_e32 v0, 31, v65
	s_addc_u32 s3, s3, 0
	v_and_b32_e32 v2, 15, v65
	v_mul_u32_u24_e32 v153, 0x110, v0
	v_mul_u32_u24_e32 v180, 0x88, v0
	v_lshl_add_u64 v[0:1], s[2:3], 0, v[68:69]
	v_lshlrev_b32_e32 v2, 4, v2
	v_mov_b32_e32 v3, v161
	v_lshl_add_u64 v[154:155], v[0:1], 0, v[2:3]
	v_lshl_add_u64 v[0:1], s[2:3], 0, v[70:71]
	s_add_u32 s2, s19, 0x21100080
	v_lshl_add_u64 v[156:157], v[0:1], 0, v[2:3]
	s_addc_u32 s3, 0, 0
	v_and_b32_e32 v2, 7, v65
	v_lshl_add_u64 v[0:1], s[2:3], 0, v[72:73]
	v_lshlrev_b32_e32 v2, 4, v2
	v_lshl_add_u64 v[158:159], v[0:1], 0, v[2:3]
	v_lshl_add_u64 v[0:1], s[2:3], 0, v[74:75]
	s_add_u32 s2, s18, 0x23e08000
	s_addc_u32 s3, 0, 0
	v_mov_b32_e32 v149, 0
	v_lshlrev_b32_e32 v151, 3, v76
	v_lshl_add_u64 v[170:171], v[0:1], 0, v[2:3]
	v_lshl_add_u64 v[172:173], v[66:67], 3, s[2:3]
	s_mov_b32 s18, 0
	v_mov_b32_e32 v0, 0
	v_mov_b32_e32 v1, v149
	v_mov_b32_e32 v2, v149
	v_mov_b32_e32 v3, v149
	v_mov_b32_e32 v4, v149
	v_mov_b32_e32 v5, v149
	v_mov_b32_e32 v6, v149
	v_mov_b32_e32 v7, v149
	v_mov_b32_e32 v8, v149
	v_mov_b32_e32 v9, v149
	v_mov_b32_e32 v10, v149
	v_mov_b32_e32 v11, v149
	v_mov_b32_e32 v12, v149
	v_mov_b32_e32 v13, v149
	v_mov_b32_e32 v14, v149
	v_mov_b32_e32 v15, v149
	v_mov_b32_e32 v16, 0
	v_mov_b32_e32 v17, v149
	v_mov_b32_e32 v18, v149
	v_mov_b32_e32 v19, v149
	v_mov_b32_e32 v20, v149
	v_mov_b32_e32 v21, v149
	v_mov_b32_e32 v22, v149
	v_mov_b32_e32 v23, v149
	v_mov_b32_e32 v24, v149
	v_mov_b32_e32 v25, v149
	v_mov_b32_e32 v26, v149
	v_mov_b32_e32 v27, v149
	v_mov_b32_e32 v28, v149
	v_mov_b32_e32 v29, v149
	v_mov_b32_e32 v30, v149
	v_mov_b32_e32 v31, v149
	v_mov_b32_e32 v32, 0
	v_mov_b32_e32 v33, v149
	v_mov_b32_e32 v34, v149
	v_mov_b32_e32 v35, v149
	v_mov_b32_e32 v36, v149
	v_mov_b32_e32 v37, v149
	v_mov_b32_e32 v38, v149
	v_mov_b32_e32 v39, v149
	v_mov_b32_e32 v40, v149
	v_mov_b32_e32 v41, v149
	v_mov_b32_e32 v42, v149
	v_mov_b32_e32 v43, v149
	v_mov_b32_e32 v44, v149
	v_mov_b32_e32 v45, v149
	v_mov_b32_e32 v46, v149
	v_mov_b32_e32 v47, v149
	v_mov_b32_e32 v48, 0
	v_mov_b32_e32 v49, v149
	v_mov_b32_e32 v50, v149
	v_mov_b32_e32 v51, v149
	v_mov_b32_e32 v52, v149
	v_mov_b32_e32 v53, v149
	v_mov_b32_e32 v54, v149
	v_mov_b32_e32 v55, v149
	v_mov_b32_e32 v56, v149
	v_mov_b32_e32 v57, v149
	v_mov_b32_e32 v58, v149
	v_mov_b32_e32 v59, v149
	v_mov_b32_e32 v60, v149
	v_mov_b32_e32 v61, v149
	v_mov_b32_e32 v62, v149
	v_mov_b32_e32 v63, v149
	s_waitcnt vmcnt(0)
	v_mov_b64_e32 v[174:175], v[176:177]
	v_readfirstlane_b32 s20, v186
	s_mov_b32 s21, 0
	s_mov_b32 s23, 0x8800
	s_mov_b32 s24, 0x11000
	s_bfe_u32 s20, s20, 0x10008
	s_cmp_eq_u32 s20, 0
	s_cbranch_scc1 .Lat_top
	s_mov_b32 s2, 0xffff8000
	s_mov_b32 s3, -1
	v_lshl_add_u64 v[172:173], v[172:173], 0, s[2:3]
	s_nop 0
.Lat_top:
	s_cmp_lt_i32 s18, s16
	s_cbranch_scc0 .Lat_noload
	v_lshl_add_u64 v[212:213], s[0:1], 0, v[154:155]
	v_lshl_add_u64 v[214:215], s[0:1], 0, v[156:157]
	v_lshl_add_u64 v[216:217], s[0:1], 0, v[158:159]
	v_lshl_add_u64 v[218:219], s[0:1], 0, v[170:171]
	global_load_dwordx4 v[96:99], v[212:213], off
	global_load_dwordx4 v[100:103], v[214:215], off
	global_load_dwordx4 v[104:107], v[216:217], off
	global_load_dwordx4 v[108:111], v[218:219], off
	v_lshl_add_u64 v[154:155], v[154:155], 0, s[30:31]
	v_lshl_add_u64 v[156:157], v[156:157], 0, s[30:31]
	v_lshl_add_u64 v[158:159], v[158:159], 0, s[78:79]
	v_lshl_add_u64 v[170:171], v[170:171], 0, s[78:79]
.Lat_noload:
	s_add_i32 s2, s16, s20
	s_cmp_lt_i32 s18, s2
	s_cbranch_scc0 .Lat_nomask
	v_lshl_add_u64 v[212:213], s[0:1], 0, v[172:173]
	global_load_dwordx2 v[174:175], v[212:213], off
	v_lshl_add_u64 v[172:173], v[172:173], 0, s[30:31]
; #define LAS __attribute__((address_space(3)))
; template <bool MASK>
; DI void attn_unit(LAS unsigned char* lds, const bf16_t* qrow, const bf16_t* kbase, int kpitch, const bf16_t* vtbase, int vtpitch, int ntiles,
;                   const unsigned long long* maskp, bf16_t* orow, float c1, float c2) {
;     ...
;         for (int sub = 0; sub < 2; ++sub) {
; #pragma unroll
;             for (int i = 0; i < 16; ++i) xs[sub][i] = 0.f;
;             __builtin_amdgcn_s_setprio(1);
; #pragma unroll
;             for (int ks = 0; ks < 8; ++ks) {
;                 const bf16x8 a = *(const LAS bf16x8*)(buf + (32 * sub + r) * AK_PITCH + ks * 32 + h * 16);
;                 xs[sub] = __builtin_amdgcn_mfma_f32_32x32x16_bf16(a, qf[ks], xs[sub], 0, 0, 0);
;             }
;             __builtin_amdgcn_s_setprio(0);
;         }
; #pragma unroll
;         for (int sub = 0; sub < 2; ++sub) {
;             const unsigned mws = ((unsigned)(mw >> (32 * sub))) >> (4 * h);
;             float pe[16];
; #pragma unroll
;             for (int i = 0; i < 16; ++i) {
;                 float p = __builtin_amdgcn_exp2f(xs[sub][i] * c1 - c2);
;                 if (MASK) { const int m = __builtin_amdgcn_sbfe((int)mws, (i & 3) + 8 * (i >> 2), 1); p = __uint_as_float(__float_as_uint(p) & (unsigned)m); }
;                 l += p; pe[i] = p;
;             }
;             u32x4 p0, p1;
;             p0.x = pk2(pe[0], pe[1]); p0.y = pk2(pe[2], pe[3]); p0.z = pk2(pe[4], pe[5]); p0.w = pk2(pe[6], pe[7]);
;             p1.x = pk2(pe[8], pe[9]); p1.y = pk2(pe[10], pe[11]); p1.z = pk2(pe[12], pe[13]); p1.w = pk2(pe[14], pe[15]);
;             const bf16x8 pb0 = __builtin_bit_cast(bf16x8, p0), pb1 = __builtin_bit_cast(bf16x8, p1);
; #pragma unroll
;             for (int dt = 0; dt < 4; ++dt) {
;                 const LAS unsigned char* vp = buf + AK_BYTES + (32 * dt + r) * AV_PITCH + (32 * sub + 4 * h) * 2;
;                 const s16x4 lo0 = *(const LAS s16x4*)(vp), hi0 = *(const LAS s16x4*)(vp + 16);
;                 const s16x4 lo1 = *(const LAS s16x4*)(vp + 32), hi1 = *(const LAS s16x4*)(vp + 48);
;                 const bf16x8 va0 = __builtin_shufflevector(lo0, hi0, 0, 1, 2, 3, 4, 5, 6, 7);
;                 const bf16x8 va1 = __builtin_shufflevector(lo1, hi1, 0, 1, 2, 3, 4, 5, 6, 7);
;                 o[dt] = __builtin_amdgcn_mfma_f32_32x32x16_bf16(va0, pb0, o[dt], 0, 0, 0);
.Lat_nomask:
	s_cmp_eq_u32 s20, 0
	s_cbranch_scc0 .Lat_grpb
	s_cmp_eq_u32 s18, 0
	s_cbranch_scc1 .Lat_a_first
	s_cmp_lt_i32 s18, s17
	s_cbranch_scc0 .Lat_a_last
	v_add3_u32 v167, s24, v151, v180
	v_add_u32_e32 v168, 0x5000, v167
	v_add_u32_e32 v169, 0x6000, v167
	v_add_u32_e32 v199, 0x7000, v167
	v_add_u32_e32 v167, 0x4000, v167
	v_add3_u32 v166, s21, v160, v153
	ds_read2_b64 v[212:215], v167 offset0:128 offset1:130
	ds_read2_b64 v[216:219], v167 offset0:132 offset1:134
	ds_read2_b64 v[220:223], v168 offset0:160 offset1:162
	ds_read2_b64 v[224:227], v168 offset0:164 offset1:166
	ds_read2_b64 v[228:231], v169 offset0:192 offset1:194
	ds_read2_b64 v[232:235], v169 offset0:196 offset1:198
	ds_read2_b64 v[236:239], v199 offset0:224 offset1:226
	ds_read2_b64 v[240:243], v199 offset0:228 offset1:230
	ds_read2_b64 v[244:247], v167 offset0:136 offset1:138
	ds_read2_b64 v[248:251], v167 offset0:140 offset1:142
	s_waitcnt lgkmcnt(9)
	v_mfma_f32_32x32x16_bf16 v[48:63], v[212:215], v[182:185], v[48:63]
	ds_read2_b64 v[212:215], v168 offset0:168 offset1:170
	s_waitcnt lgkmcnt(9)
	v_mfma_f32_32x32x16_bf16 v[48:63], v[216:219], v[200:203], v[48:63]
	ds_read2_b64 v[216:219], v168 offset0:172 offset1:174
	s_waitcnt lgkmcnt(9)
	v_mfma_f32_32x32x16_bf16 v[32:47], v[220:223], v[182:185], v[32:47]
	ds_read2_b64 v[220:223], v169 offset0:200 offset1:202
	s_waitcnt lgkmcnt(9)
	v_mfma_f32_32x32x16_bf16 v[32:47], v[224:227], v[200:203], v[32:47]
	ds_read2_b64 v[224:227], v169 offset0:204 offset1:206
	s_waitcnt lgkmcnt(9)
	v_mfma_f32_32x32x16_bf16 v[16:31], v[228:231], v[182:185], v[16:31]
	ds_read2_b64 v[228:231], v199 offset0:232 offset1:234
	s_waitcnt lgkmcnt(9)
	v_mfma_f32_32x32x16_bf16 v[16:31], v[232:235], v[200:203], v[16:31]
	ds_read2_b64 v[232:235], v199 offset0:236 offset1:238
	s_waitcnt lgkmcnt(9)
	v_mfma_f32_32x32x16_bf16 v[0:15], v[236:239], v[182:185], v[0:15]
	ds_read_b128 v[236:239], v166
	s_waitcnt lgkmcnt(9)
	v_mfma_f32_32x32x16_bf16 v[0:15], v[240:243], v[200:203], v[0:15]
	ds_read_b128 v[240:243], v166 offset:32
	s_waitcnt lgkmcnt(9)
	v_mfma_f32_32x32x16_bf16 v[48:63], v[244:247], v[204:207], v[48:63]
	ds_read_b128 v[244:247], v166 offset:64
	s_waitcnt lgkmcnt(9)
	v_mfma_f32_32x32x16_bf16 v[48:63], v[248:251], v[208:211], v[48:63]
	ds_read_b128 v[248:251], v166 offset:96
	s_waitcnt lgkmcnt(9)
	v_mfma_f32_32x32x16_bf16 v[32:47], v[212:215], v[204:207], v[32:47]
	ds_read_b128 v[212:215], v166 offset:128
	s_waitcnt lgkmcnt(9)
	v_mfma_f32_32x32x16_bf16 v[32:47], v[216:219], v[208:211], v[32:47]
	ds_read_b128 v[216:219], v166 offset:160
	s_waitcnt lgkmcnt(9)
	v_mfma_f32_32x32x16_bf16 v[16:31], v[220:223], v[204:207], v[16:31]
	ds_read_b128 v[220:223], v166 offset:192
	s_waitcnt lgkmcnt(9)
	v_mfma_f32_32x32x16_bf16 v[16:31], v[224:227], v[208:211], v[16:31]
	ds_read_b128 v[224:227], v166 offset:224
	s_waitcnt lgkmcnt(9)
	v_mfma_f32_32x32x16_bf16 v[0:15], v[228:231], v[204:207], v[0:15]
	ds_read_b128 v[228:231], v166 offset:8704
	s_waitcnt lgkmcnt(9)
	v_mfma_f32_32x32x16_bf16 v[0:15], v[232:235], v[208:211], v[0:15]
	ds_read_b128 v[232:235], v166 offset:8736
	s_waitcnt lgkmcnt(9)
	v_mfma_f32_32x32x16_bf16 v[80:95], v[236:239], v[112:115], 0
	ds_read_b128 v[236:239], v166 offset:8768
	s_waitcnt lgkmcnt(9)
	v_mfma_f32_32x32x16_bf16 v[80:95], v[240:243], v[116:119], v[80:95]
	ds_read_b128 v[240:243], v166 offset:8800
	s_waitcnt lgkmcnt(9)
	v_mfma_f32_32x32x16_bf16 v[80:95], v[244:247], v[120:123], v[80:95]
	ds_read_b128 v[244:247], v166 offset:8832
	s_waitcnt lgkmcnt(9)
	v_mfma_f32_32x32x16_bf16 v[80:95], v[248:251], v[124:127], v[80:95]
	ds_read_b128 v[248:251], v166 offset:8864
	s_waitcnt lgkmcnt(9)
	v_mfma_f32_32x32x16_bf16 v[80:95], v[212:215], v[128:131], v[80:95]
	ds_read_b128 v[212:215], v166 offset:8896
	s_waitcnt lgkmcnt(9)
	v_mfma_f32_32x32x16_bf16 v[80:95], v[216:219], v[132:135], v[80:95]
	ds_read_b128 v[216:219], v166 offset:8928
	s_waitcnt lgkmcnt(9)
	v_mfma_f32_32x32x16_bf16 v[80:95], v[220:223], v[136:139], v[80:95]
	s_waitcnt lgkmcnt(8)
	v_mfma_f32_32x32x16_bf16 v[80:95], v[224:227], v[140:143], v[80:95]
	s_waitcnt lgkmcnt(7)
	v_mfma_f32_32x32x16_bf16 v[64:79], v[228:231], v[112:115], 0
	s_waitcnt lgkmcnt(6)
	v_mfma_f32_32x32x16_bf16 v[64:79], v[232:235], v[116:119], v[64:79]
	s_waitcnt lgkmcnt(5)
	v_mfma_f32_32x32x16_bf16 v[64:79], v[236:239], v[120:123], v[64:79]
	s_waitcnt lgkmcnt(4)
	v_mfma_f32_32x32x16_bf16 v[64:79], v[240:243], v[124:127], v[64:79]
	s_waitcnt lgkmcnt(3)
	v_mfma_f32_32x32x16_bf16 v[64:79], v[244:247], v[128:131], v[64:79]
	s_waitcnt lgkmcnt(2)
	v_mfma_f32_32x32x16_bf16 v[64:79], v[248:251], v[132:135], v[64:79]
	s_waitcnt lgkmcnt(1)
	v_mfma_f32_32x32x16_bf16 v[64:79], v[212:215], v[136:139], v[64:79]
	s_waitcnt lgkmcnt(0)
; DI unsigned pk2(float lo, float hi) { f32x2 v = {lo, hi}; bf16x2_t b = __builtin_convertvector(v, bf16x2_t); return __builtin_bit_cast(unsigned, b); }
; template <bool MASK>
; DI void attn_unit(LAS unsigned char* lds, const bf16_t* qrow, const bf16_t* kbase, int kpitch, const bf16_t* vtbase, int vtpitch, int ntiles,
;                   const unsigned long long* maskp, bf16_t* orow, float c1, float c2) {
;     ...
;         for (int sub = 0; sub < 2; ++sub) {
;             const unsigned mws = ((unsigned)(mw >> (32 * sub))) >> (4 * h);
;             float pe[16];
; #pragma unroll
;             for (int i = 0; i < 16; ++i) {
;                 float p = __builtin_amdgcn_exp2f(xs[sub][i] * c1 - c2);
;                 if (MASK) { const int m = __builtin_amdgcn_sbfe((int)mws, (i & 3) + 8 * (i >> 2), 1); p = __uint_as_float(__float_as_uint(p) & (unsigned)m); }
;                 l += p; pe[i] = p;
;             }
;             u32x4 p0, p1;
;             p0.x = pk2(pe[0], pe[1]); p0.y = pk2(pe[2], pe[3]); p0.z = pk2(pe[4], pe[5]); p0.w = pk2(pe[6], pe[7]);
;             p1.x = pk2(pe[8], pe[9]); p1.y = pk2(pe[10], pe[11]); p1.z = pk2(pe[12], pe[13]); p1.w = pk2(pe[14], pe[15]);
	v_mfma_f32_32x32x16_bf16 v[64:79], v[216:219], v[140:143], v[64:79]
	v_lshrrev_b32_e32 v212, v147, v176
	v_lshrrev_b32_e32 v213, v147, v177
	v_fma_f32 v80, v80, s95, -v178
	v_exp_f32_e32 v80, v80
	v_bfe_i32 v214, v212, 0, 1
	v_fma_f32 v81, v81, s95, -v178
	v_exp_f32_e32 v81, v81
	v_bfe_i32 v215, v212, 1, 1
	v_and_b32_e32 v80, v80, v214
	v_fma_f32 v82, v82, s95, -v178
	v_exp_f32_e32 v82, v82
	v_bfe_i32 v216, v212, 2, 1
	v_and_b32_e32 v81, v81, v215
	v_fma_f32 v83, v83, s95, -v178
	v_exp_f32_e32 v83, v83
	v_bfe_i32 v217, v212, 3, 1
	v_and_b32_e32 v82, v82, v216
	v_fma_f32 v84, v84, s95, -v178
	v_exp_f32_e32 v84, v84
	v_bfe_i32 v218, v212, 8, 1
	v_and_b32_e32 v83, v83, v217
	v_fma_f32 v85, v85, s95, -v178
	v_exp_f32_e32 v85, v85
	v_bfe_i32 v219, v212, 9, 1
	v_and_b32_e32 v84, v84, v218
	v_fma_f32 v86, v86, s95, -v178
	v_exp_f32_e32 v86, v86
	v_bfe_i32 v214, v212, 10, 1
	v_and_b32_e32 v85, v85, v219
	v_fma_f32 v87, v87, s95, -v178
	v_exp_f32_e32 v87, v87
	v_bfe_i32 v215, v212, 11, 1
	v_and_b32_e32 v86, v86, v214
	v_fma_f32 v88, v88, s95, -v178
	v_exp_f32_e32 v88, v88
	v_bfe_i32 v216, v212, 16, 1
	v_and_b32_e32 v87, v87, v215
	v_fma_f32 v89, v89, s95, -v178
	v_exp_f32_e32 v89, v89
	v_bfe_i32 v217, v212, 17, 1
	v_and_b32_e32 v88, v88, v216
	v_fma_f32 v90, v90, s95, -v178
	v_exp_f32_e32 v90, v90
	v_bfe_i32 v218, v212, 18, 1
	v_and_b32_e32 v89, v89, v217
	v_fma_f32 v91, v91, s95, -v178
	v_exp_f32_e32 v91, v91
	v_bfe_i32 v219, v212, 19, 1
	v_and_b32_e32 v90, v90, v218
	v_fma_f32 v92, v92, s95, -v178
	v_exp_f32_e32 v92, v92
	v_bfe_i32 v214, v212, 24, 1
	v_and_b32_e32 v91, v91, v219
	v_fma_f32 v93, v93, s95, -v178
	v_exp_f32_e32 v93, v93
	v_bfe_i32 v215, v212, 25, 1
	v_and_b32_e32 v92, v92, v214
	v_fma_f32 v94, v94, s95, -v178
	v_exp_f32_e32 v94, v94
	v_bfe_i32 v216, v212, 26, 1
	v_and_b32_e32 v93, v93, v215
	v_fma_f32 v95, v95, s95, -v178
	v_exp_f32_e32 v95, v95
	v_bfe_i32 v217, v212, 27, 1
	v_and_b32_e32 v94, v94, v216
	v_nop
	v_and_b32_e32 v95, v95, v217
	v_cvt_pk_bf16_f32 v182, v80, v81
	v_cvt_pk_bf16_f32 v183, v82, v83
	v_cvt_pk_bf16_f32 v184, v84, v85
	v_cvt_pk_bf16_f32 v185, v86, v87
	v_cvt_pk_bf16_f32 v200, v88, v89
	v_cvt_pk_bf16_f32 v201, v90, v91
	v_cvt_pk_bf16_f32 v202, v92, v93
	v_cvt_pk_bf16_f32 v203, v94, v95
	v_pk_add_f32 v[80:81], v[80:81], v[82:83]
	v_pk_add_f32 v[84:85], v[84:85], v[86:87]
	v_pk_add_f32 v[88:89], v[88:89], v[90:91]
	v_pk_add_f32 v[92:93], v[92:93], v[94:95]
	v_pk_add_f32 v[80:81], v[80:81], v[84:85]
	v_pk_add_f32 v[88:89], v[88:89], v[92:93]
	v_pk_add_f32 v[80:81], v[80:81], v[88:89]
	v_add_f32_e32 v80, v80, v81
	v_add_f32_e32 v149, v149, v80
	v_fma_f32 v64, v64, s95, -v178
	v_exp_f32_e32 v64, v64
	v_bfe_i32 v214, v213, 0, 1
	v_fma_f32 v65, v65, s95, -v178
	v_exp_f32_e32 v65, v65
	v_bfe_i32 v215, v213, 1, 1
	v_and_b32_e32 v64, v64, v214
	v_fma_f32 v66, v66, s95, -v178
	v_exp_f32_e32 v66, v66
	v_bfe_i32 v216, v213, 2, 1
	v_and_b32_e32 v65, v65, v215
	v_fma_f32 v67, v67, s95, -v178
	v_exp_f32_e32 v67, v67
	v_bfe_i32 v217, v213, 3, 1
	v_and_b32_e32 v66, v66, v216
	v_fma_f32 v68, v68, s95, -v178
	v_exp_f32_e32 v68, v68
	v_bfe_i32 v218, v213, 8, 1
	v_and_b32_e32 v67, v67, v217
	v_fma_f32 v69, v69, s95, -v178
	v_exp_f32_e32 v69, v69
	v_bfe_i32 v219, v213, 9, 1
	v_and_b32_e32 v68, v68, v218
	v_fma_f32 v70, v70, s95, -v178
	v_exp_f32_e32 v70, v70
	v_bfe_i32 v214, v213, 10, 1
	v_and_b32_e32 v69, v69, v219
	v_fma_f32 v71, v71, s95, -v178
	v_exp_f32_e32 v71, v71
	v_bfe_i32 v215, v213, 11, 1
	v_and_b32_e32 v70, v70, v214
	v_fma_f32 v72, v72, s95, -v178
	v_exp_f32_e32 v72, v72
	v_bfe_i32 v216, v213, 16, 1
	v_and_b32_e32 v71, v71, v215
	v_fma_f32 v73, v73, s95, -v178
	v_exp_f32_e32 v73, v73
	v_bfe_i32 v217, v213, 17, 1
	v_and_b32_e32 v72, v72, v216
	v_fma_f32 v74, v74, s95, -v178
	v_exp_f32_e32 v74, v74
	v_bfe_i32 v218, v213, 18, 1
	v_and_b32_e32 v73, v73, v217
	v_fma_f32 v75, v75, s95, -v178
	v_exp_f32_e32 v75, v75
	v_bfe_i32 v219, v213, 19, 1
	v_and_b32_e32 v74, v74, v218
	v_fma_f32 v76, v76, s95, -v178
	v_exp_f32_e32 v76, v76
	v_bfe_i32 v214, v213, 24, 1
	v_and_b32_e32 v75, v75, v219
	v_fma_f32 v77, v77, s95, -v178
	v_exp_f32_e32 v77, v77
	v_bfe_i32 v215, v213, 25, 1
	v_and_b32_e32 v76, v76, v214
	v_fma_f32 v78, v78, s95, -v178
	v_exp_f32_e32 v78, v78
	v_bfe_i32 v216, v213, 26, 1
	v_and_b32_e32 v77, v77, v215
	v_fma_f32 v79, v79, s95, -v178
	v_exp_f32_e32 v79, v79
	v_bfe_i32 v217, v213, 27, 1
	v_and_b32_e32 v78, v78, v216
	v_nop
	v_and_b32_e32 v79, v79, v217
	v_cvt_pk_bf16_f32 v204, v64, v65
	v_cvt_pk_bf16_f32 v205, v66, v67
	v_cvt_pk_bf16_f32 v206, v68, v69
	v_cvt_pk_bf16_f32 v207, v70, v71
	v_cvt_pk_bf16_f32 v208, v72, v73
	v_cvt_pk_bf16_f32 v209, v74, v75
	v_cvt_pk_bf16_f32 v210, v76, v77
	v_cvt_pk_bf16_f32 v211, v78, v79
	v_pk_add_f32 v[64:65], v[64:65], v[66:67]
	v_pk_add_f32 v[68:69], v[68:69], v[70:71]
	v_pk_add_f32 v[72:73], v[72:73], v[74:75]
	v_pk_add_f32 v[76:77], v[76:77], v[78:79]
	v_pk_add_f32 v[64:65], v[64:65], v[68:69]
	v_pk_add_f32 v[72:73], v[72:73], v[76:77]
	v_pk_add_f32 v[64:65], v[64:65], v[72:73]
	v_add_f32_e32 v64, v64, v65
	v_add_f32_e32 v149, v149, v64
	s_branch .Lat_bottom
; #define LAS __attribute__((address_space(3)))
; DI unsigned pk2(float lo, float hi) { f32x2 v = {lo, hi}; bf16x2_t b = __builtin_convertvector(v, bf16x2_t); return __builtin_bit_cast(unsigned, b); }
; template <bool MASK>
; DI void attn_unit(LAS unsigned char* lds, const bf16_t* qrow, const bf16_t* kbase, int kpitch, const bf16_t* vtbase, int vtpitch, int ntiles,
;                   const unsigned long long* maskp, bf16_t* orow, float c1, float c2) {
;     ...
; #pragma unroll
;         for (int sub = 0; sub < 2; ++sub) {
; #pragma unroll
;             for (int i = 0; i < 16; ++i) xs[sub][i] = 0.f;
;             __builtin_amdgcn_s_setprio(1);
; #pragma unroll
;             for (int ks = 0; ks < 8; ++ks) {
;                 const bf16x8 a = *(const LAS bf16x8*)(buf + (32 * sub + r) * AK_PITCH + ks * 32 + h * 16);
;                 xs[sub] = __builtin_amdgcn_mfma_f32_32x32x16_bf16(a, qf[ks], xs[sub], 0, 0, 0);
;             }
;             __builtin_amdgcn_s_setprio(0);
;         }
; #pragma unroll
;         for (int sub = 0; sub < 2; ++sub) {
;             const unsigned mws = ((unsigned)(mw >> (32 * sub))) >> (4 * h);
;             float pe[16];
; #pragma unroll
;             for (int i = 0; i < 16; ++i) {
;                 float p = __builtin_amdgcn_exp2f(xs[sub][i] * c1 - c2);
;                 if (MASK) { const int m = __builtin_amdgcn_sbfe((int)mws, (i & 3) + 8 * (i >> 2), 1); p = __uint_as_float(__float_as_uint(p) & (unsigned)m); }
;                 l += p; pe[i] = p;
;             }
;             u32x4 p0, p1;
;             p0.x = pk2(pe[0], pe[1]); p0.y = pk2(pe[2], pe[3]); p0.z = pk2(pe[4], pe[5]); p0.w = pk2(pe[6], pe[7]);
;             p1.x = pk2(pe[8], pe[9]); p1.y = pk2(pe[10], pe[11]); p1.z = pk2(pe[12], pe[13]); p1.w = pk2(pe[14], pe[15]);
.Lat_a_first:
	v_add3_u32 v166, s21, v160, v153
	ds_read_b128 v[212:215], v166
	ds_read_b128 v[216:219], v166 offset:32
	ds_read_b128 v[220:223], v166 offset:64
	ds_read_b128 v[224:227], v166 offset:96
	ds_read_b128 v[228:231], v166 offset:128
	ds_read_b128 v[232:235], v166 offset:160
	ds_read_b128 v[236:239], v166 offset:192
	ds_read_b128 v[240:243], v166 offset:224
	ds_read_b128 v[244:247], v166 offset:8704
	ds_read_b128 v[248:251], v166 offset:8736
	s_waitcnt lgkmcnt(9)
	v_mfma_f32_32x32x16_bf16 v[80:95], v[212:215], v[112:115], 0
	ds_read_b128 v[212:215], v166 offset:8768
	s_waitcnt lgkmcnt(9)
	v_mfma_f32_32x32x16_bf16 v[80:95], v[216:219], v[116:119], v[80:95]
	ds_read_b128 v[216:219], v166 offset:8800
	s_waitcnt lgkmcnt(9)
	v_mfma_f32_32x32x16_bf16 v[80:95], v[220:223], v[120:123], v[80:95]
	ds_read_b128 v[220:223], v166 offset:8832
	s_waitcnt lgkmcnt(9)
	v_mfma_f32_32x32x16_bf16 v[80:95], v[224:227], v[124:127], v[80:95]
	ds_read_b128 v[224:227], v166 offset:8864
	s_waitcnt lgkmcnt(9)
	v_mfma_f32_32x32x16_bf16 v[80:95], v[228:231], v[128:131], v[80:95]
	ds_read_b128 v[228:231], v166 offset:8896
	s_waitcnt lgkmcnt(9)
	v_mfma_f32_32x32x16_bf16 v[80:95], v[232:235], v[132:135], v[80:95]
	ds_read_b128 v[232:235], v166 offset:8928
	s_waitcnt lgkmcnt(9)
	v_mfma_f32_32x32x16_bf16 v[80:95], v[236:239], v[136:139], v[80:95]
	s_waitcnt lgkmcnt(8)
	v_mfma_f32_32x32x16_bf16 v[80:95], v[240:243], v[140:143], v[80:95]
	s_waitcnt lgkmcnt(7)
	v_mfma_f32_32x32x16_bf16 v[64:79], v[244:247], v[112:115], 0
	s_waitcnt lgkmcnt(6)
	v_mfma_f32_32x32x16_bf16 v[64:79], v[248:251], v[116:119], v[64:79]
	s_waitcnt lgkmcnt(5)
	v_mfma_f32_32x32x16_bf16 v[64:79], v[212:215], v[120:123], v[64:79]
	s_waitcnt lgkmcnt(4)
	v_mfma_f32_32x32x16_bf16 v[64:79], v[216:219], v[124:127], v[64:79]
	s_waitcnt lgkmcnt(3)
	v_mfma_f32_32x32x16_bf16 v[64:79], v[220:223], v[128:131], v[64:79]
	s_waitcnt lgkmcnt(2)
	v_mfma_f32_32x32x16_bf16 v[64:79], v[224:227], v[132:135], v[64:79]
	s_waitcnt lgkmcnt(1)
	v_mfma_f32_32x32x16_bf16 v[64:79], v[228:231], v[136:139], v[64:79]
	s_waitcnt lgkmcnt(0)
	v_mfma_f32_32x32x16_bf16 v[64:79], v[232:235], v[140:143], v[64:79]
	v_lshrrev_b32_e32 v212, v147, v176
	v_lshrrev_b32_e32 v213, v147, v177
	v_fma_f32 v80, v80, s95, -v178
	v_exp_f32_e32 v80, v80
	v_bfe_i32 v214, v212, 0, 1
	v_fma_f32 v81, v81, s95, -v178
	v_exp_f32_e32 v81, v81
	v_bfe_i32 v215, v212, 1, 1
	v_and_b32_e32 v80, v80, v214
	v_fma_f32 v82, v82, s95, -v178
	v_exp_f32_e32 v82, v82
	v_bfe_i32 v216, v212, 2, 1
	v_and_b32_e32 v81, v81, v215
	v_fma_f32 v83, v83, s95, -v178
	v_exp_f32_e32 v83, v83
	v_bfe_i32 v217, v212, 3, 1
	v_and_b32_e32 v82, v82, v216
	v_fma_f32 v84, v84, s95, -v178
	v_exp_f32_e32 v84, v84
	v_bfe_i32 v218, v212, 8, 1
	v_and_b32_e32 v83, v83, v217
	v_fma_f32 v85, v85, s95, -v178
	v_exp_f32_e32 v85, v85
	v_bfe_i32 v219, v212, 9, 1
	v_and_b32_e32 v84, v84, v218
	v_fma_f32 v86, v86, s95, -v178
	v_exp_f32_e32 v86, v86
	v_bfe_i32 v214, v212, 10, 1
	v_and_b32_e32 v85, v85, v219
	v_fma_f32 v87, v87, s95, -v178
	v_exp_f32_e32 v87, v87
	v_bfe_i32 v215, v212, 11, 1
	v_and_b32_e32 v86, v86, v214
	v_fma_f32 v88, v88, s95, -v178
	v_exp_f32_e32 v88, v88
	v_bfe_i32 v216, v212, 16, 1
	v_and_b32_e32 v87, v87, v215
	v_fma_f32 v89, v89, s95, -v178
	v_exp_f32_e32 v89, v89
	v_bfe_i32 v217, v212, 17, 1
	v_and_b32_e32 v88, v88, v216
	v_fma_f32 v90, v90, s95, -v178
	v_exp_f32_e32 v90, v90
	v_bfe_i32 v218, v212, 18, 1
	v_and_b32_e32 v89, v89, v217
	v_fma_f32 v91, v91, s95, -v178
	v_exp_f32_e32 v91, v91
	v_bfe_i32 v219, v212, 19, 1
	v_and_b32_e32 v90, v90, v218
	v_fma_f32 v92, v92, s95, -v178
	v_exp_f32_e32 v92, v92
	v_bfe_i32 v214, v212, 24, 1
	v_and_b32_e32 v91, v91, v219
	v_fma_f32 v93, v93, s95, -v178
	v_exp_f32_e32 v93, v93
	v_bfe_i32 v215, v212, 25, 1
	v_and_b32_e32 v92, v92, v214
	v_fma_f32 v94, v94, s95, -v178
	v_exp_f32_e32 v94, v94
	v_bfe_i32 v216, v212, 26, 1
	v_and_b32_e32 v93, v93, v215
	v_fma_f32 v95, v95, s95, -v178
	v_exp_f32_e32 v95, v95
	v_bfe_i32 v217, v212, 27, 1
	v_and_b32_e32 v94, v94, v216
	v_nop
	v_and_b32_e32 v95, v95, v217
	v_cvt_pk_bf16_f32 v182, v80, v81
	v_cvt_pk_bf16_f32 v183, v82, v83
	v_cvt_pk_bf16_f32 v184, v84, v85
	v_cvt_pk_bf16_f32 v185, v86, v87
	v_cvt_pk_bf16_f32 v200, v88, v89
	v_cvt_pk_bf16_f32 v201, v90, v91
	v_cvt_pk_bf16_f32 v202, v92, v93
	v_cvt_pk_bf16_f32 v203, v94, v95
	v_pk_add_f32 v[80:81], v[80:81], v[82:83]
	v_pk_add_f32 v[84:85], v[84:85], v[86:87]
	v_pk_add_f32 v[88:89], v[88:89], v[90:91]
	v_pk_add_f32 v[92:93], v[92:93], v[94:95]
	v_pk_add_f32 v[80:81], v[80:81], v[84:85]
	v_pk_add_f32 v[88:89], v[88:89], v[92:93]
	v_pk_add_f32 v[80:81], v[80:81], v[88:89]
	v_add_f32_e32 v80, v80, v81
	v_add_f32_e32 v149, v149, v80
	v_fma_f32 v64, v64, s95, -v178
	v_exp_f32_e32 v64, v64
	v_bfe_i32 v214, v213, 0, 1
	v_fma_f32 v65, v65, s95, -v178
	v_exp_f32_e32 v65, v65
	v_bfe_i32 v215, v213, 1, 1
	v_and_b32_e32 v64, v64, v214
	v_fma_f32 v66, v66, s95, -v178
	v_exp_f32_e32 v66, v66
	v_bfe_i32 v216, v213, 2, 1
	v_and_b32_e32 v65, v65, v215
	v_fma_f32 v67, v67, s95, -v178
	v_exp_f32_e32 v67, v67
	v_bfe_i32 v217, v213, 3, 1
	v_and_b32_e32 v66, v66, v216
	v_fma_f32 v68, v68, s95, -v178
	v_exp_f32_e32 v68, v68
	v_bfe_i32 v218, v213, 8, 1
	v_and_b32_e32 v67, v67, v217
	v_fma_f32 v69, v69, s95, -v178
	v_exp_f32_e32 v69, v69
	v_bfe_i32 v219, v213, 9, 1
	v_and_b32_e32 v68, v68, v218
	v_fma_f32 v70, v70, s95, -v178
	v_exp_f32_e32 v70, v70
	v_bfe_i32 v214, v213, 10, 1
	v_and_b32_e32 v69, v69, v219
	v_fma_f32 v71, v71, s95, -v178
	v_exp_f32_e32 v71, v71
	v_bfe_i32 v215, v213, 11, 1
	v_and_b32_e32 v70, v70, v214
	v_fma_f32 v72, v72, s95, -v178
	v_exp_f32_e32 v72, v72
; #define LAS __attribute__((address_space(3)))
; DI unsigned pk2(float lo, float hi) { f32x2 v = {lo, hi}; bf16x2_t b = __builtin_convertvector(v, bf16x2_t); return __builtin_bit_cast(unsigned, b); }
; template <bool MASK>
; DI void attn_unit(LAS unsigned char* lds, const bf16_t* qrow, const bf16_t* kbase, int kpitch, const bf16_t* vtbase, int vtpitch, int ntiles,
;                   const unsigned long long* maskp, bf16_t* orow, float c1, float c2) {
;     ...
;         for (int sub = 0; sub < 2; ++sub) {
;             const unsigned mws = ((unsigned)(mw >> (32 * sub))) >> (4 * h);
;             float pe[16];
; #pragma unroll
;             for (int i = 0; i < 16; ++i) {
;                 float p = __builtin_amdgcn_exp2f(xs[sub][i] * c1 - c2);
;                 if (MASK) { const int m = __builtin_amdgcn_sbfe((int)mws, (i & 3) + 8 * (i >> 2), 1); p = __uint_as_float(__float_as_uint(p) & (unsigned)m); }
;                 l += p; pe[i] = p;
;             }
;             u32x4 p0, p1;
;             p0.x = pk2(pe[0], pe[1]); p0.y = pk2(pe[2], pe[3]); p0.z = pk2(pe[4], pe[5]); p0.w = pk2(pe[6], pe[7]);
;             p1.x = pk2(pe[8], pe[9]); p1.y = pk2(pe[10], pe[11]); p1.z = pk2(pe[12], pe[13]); p1.w = pk2(pe[14], pe[15]);
;             const bf16x8 pb0 = __builtin_bit_cast(bf16x8, p0), pb1 = __builtin_bit_cast(bf16x8, p1);
; #pragma unroll
;             for (int dt = 0; dt < 4; ++dt) {
;                 const LAS unsigned char* vp = buf + AK_BYTES + (32 * dt + r) * AV_PITCH + (32 * sub + 4 * h) * 2;
;                 const s16x4 lo0 = *(const LAS s16x4*)(vp), hi0 = *(const LAS s16x4*)(vp + 16);
;                 const s16x4 lo1 = *(const LAS s16x4*)(vp + 32), hi1 = *(const LAS s16x4*)(vp + 48);
;                 const bf16x8 va0 = __builtin_shufflevector(lo0, hi0, 0, 1, 2, 3, 4, 5, 6, 7);
;                 const bf16x8 va1 = __builtin_shufflevector(lo1, hi1, 0, 1, 2, 3, 4, 5, 6, 7);
;                 o[dt] = __builtin_amdgcn_mfma_f32_32x32x16_bf16(va0, pb0, o[dt], 0, 0, 0);
;                 o[dt] = __builtin_amdgcn_mfma_f32_32x32x16_bf16(va1, pb1, o[dt], 0, 0, 0);
;             }
	v_bfe_i32 v216, v213, 16, 1
	v_and_b32_e32 v71, v71, v215
	v_fma_f32 v73, v73, s95, -v178
	v_exp_f32_e32 v73, v73
	v_bfe_i32 v217, v213, 17, 1
	v_and_b32_e32 v72, v72, v216
	v_fma_f32 v74, v74, s95, -v178
	v_exp_f32_e32 v74, v74
	v_bfe_i32 v218, v213, 18, 1
	v_and_b32_e32 v73, v73, v217
	v_fma_f32 v75, v75, s95, -v178
	v_exp_f32_e32 v75, v75
	v_bfe_i32 v219, v213, 19, 1
	v_and_b32_e32 v74, v74, v218
	v_fma_f32 v76, v76, s95, -v178
	v_exp_f32_e32 v76, v76
	v_bfe_i32 v214, v213, 24, 1
	v_and_b32_e32 v75, v75, v219
	v_fma_f32 v77, v77, s95, -v178
	v_exp_f32_e32 v77, v77
	v_bfe_i32 v215, v213, 25, 1
	v_and_b32_e32 v76, v76, v214
	v_fma_f32 v78, v78, s95, -v178
	v_exp_f32_e32 v78, v78
	v_bfe_i32 v216, v213, 26, 1
	v_and_b32_e32 v77, v77, v215
	v_fma_f32 v79, v79, s95, -v178
	v_exp_f32_e32 v79, v79
	v_bfe_i32 v217, v213, 27, 1
	v_and_b32_e32 v78, v78, v216
	v_nop
	v_and_b32_e32 v79, v79, v217
	v_cvt_pk_bf16_f32 v204, v64, v65
	v_cvt_pk_bf16_f32 v205, v66, v67
	v_cvt_pk_bf16_f32 v206, v68, v69
	v_cvt_pk_bf16_f32 v207, v70, v71
	v_cvt_pk_bf16_f32 v208, v72, v73
	v_cvt_pk_bf16_f32 v209, v74, v75
	v_cvt_pk_bf16_f32 v210, v76, v77
	v_cvt_pk_bf16_f32 v211, v78, v79
	v_pk_add_f32 v[64:65], v[64:65], v[66:67]
	v_pk_add_f32 v[68:69], v[68:69], v[70:71]
	v_pk_add_f32 v[72:73], v[72:73], v[74:75]
	v_pk_add_f32 v[76:77], v[76:77], v[78:79]
	v_pk_add_f32 v[64:65], v[64:65], v[68:69]
	v_pk_add_f32 v[72:73], v[72:73], v[76:77]
	v_pk_add_f32 v[64:65], v[64:65], v[72:73]
	v_add_f32_e32 v64, v64, v65
	v_add_f32_e32 v149, v149, v64
	s_branch .Lat_bottom
.Lat_a_last:
	v_add3_u32 v167, s24, v151, v180
	v_add_u32_e32 v168, 0x5000, v167
	v_add_u32_e32 v169, 0x6000, v167
	v_add_u32_e32 v199, 0x7000, v167
	v_add_u32_e32 v167, 0x4000, v167
	ds_read2_b64 v[212:215], v167 offset0:128 offset1:130
	ds_read2_b64 v[216:219], v167 offset0:132 offset1:134
	ds_read2_b64 v[220:223], v168 offset0:160 offset1:162
	ds_read2_b64 v[224:227], v168 offset0:164 offset1:166
	ds_read2_b64 v[228:231], v169 offset0:192 offset1:194
	ds_read2_b64 v[232:235], v169 offset0:196 offset1:198
	ds_read2_b64 v[236:239], v199 offset0:224 offset1:226
	ds_read2_b64 v[240:243], v199 offset0:228 offset1:230
	ds_read2_b64 v[244:247], v167 offset0:136 offset1:138
	ds_read2_b64 v[248:251], v167 offset0:140 offset1:142
	s_waitcnt lgkmcnt(9)
	v_mfma_f32_32x32x16_bf16 v[48:63], v[212:215], v[182:185], v[48:63]
	ds_read2_b64 v[212:215], v168 offset0:168 offset1:170
	s_waitcnt lgkmcnt(9)
	v_mfma_f32_32x32x16_bf16 v[48:63], v[216:219], v[200:203], v[48:63]
	ds_read2_b64 v[216:219], v168 offset0:172 offset1:174
	s_waitcnt lgkmcnt(9)
	v_mfma_f32_32x32x16_bf16 v[32:47], v[220:223], v[182:185], v[32:47]
	ds_read2_b64 v[220:223], v169 offset0:200 offset1:202
	s_waitcnt lgkmcnt(9)
	v_mfma_f32_32x32x16_bf16 v[32:47], v[224:227], v[200:203], v[32:47]
	ds_read2_b64 v[224:227], v169 offset0:204 offset1:206
	s_waitcnt lgkmcnt(9)
	v_mfma_f32_32x32x16_bf16 v[16:31], v[228:231], v[182:185], v[16:31]
	ds_read2_b64 v[228:231], v199 offset0:232 offset1:234
	s_waitcnt lgkmcnt(9)
	v_mfma_f32_32x32x16_bf16 v[16:31], v[232:235], v[200:203], v[16:31]
	ds_read2_b64 v[232:235], v199 offset0:236 offset1:238
	s_waitcnt lgkmcnt(9)
	v_mfma_f32_32x32x16_bf16 v[0:15], v[236:239], v[182:185], v[0:15]
	s_waitcnt lgkmcnt(8)
	v_mfma_f32_32x32x16_bf16 v[0:15], v[240:243], v[200:203], v[0:15]
	s_waitcnt lgkmcnt(7)
	v_mfma_f32_32x32x16_bf16 v[48:63], v[244:247], v[204:207], v[48:63]
	s_waitcnt lgkmcnt(6)
	v_mfma_f32_32x32x16_bf16 v[48:63], v[248:251], v[208:211], v[48:63]
	s_waitcnt lgkmcnt(5)
	v_mfma_f32_32x32x16_bf16 v[32:47], v[212:215], v[204:207], v[32:47]
	s_waitcnt lgkmcnt(4)
	v_mfma_f32_32x32x16_bf16 v[32:47], v[216:219], v[208:211], v[32:47]
	s_waitcnt lgkmcnt(3)
	v_mfma_f32_32x32x16_bf16 v[16:31], v[220:223], v[204:207], v[16:31]
	s_waitcnt lgkmcnt(2)
	v_mfma_f32_32x32x16_bf16 v[16:31], v[224:227], v[208:211], v[16:31]
	s_waitcnt lgkmcnt(1)
	v_mfma_f32_32x32x16_bf16 v[0:15], v[228:231], v[204:207], v[0:15]
	s_waitcnt lgkmcnt(0)
	v_mfma_f32_32x32x16_bf16 v[0:15], v[232:235], v[208:211], v[0:15]
	s_branch .Lat_bottom
.Lat_grpb:
	s_cmp_eq_u32 s18, 0
	s_cbranch_scc1 .Lat_b_first
	v_lshrrev_b32_e32 v212, v147, v176
	v_lshrrev_b32_e32 v213, v147, v177
	v_fma_f32 v80, v80, s95, -v178
	v_exp_f32_e32 v80, v80
	v_bfe_i32 v214, v212, 0, 1
	v_fma_f32 v81, v81, s95, -v178
	v_exp_f32_e32 v81, v81
	v_bfe_i32 v215, v212, 1, 1
	v_and_b32_e32 v80, v80, v214
	v_fma_f32 v82, v82, s95, -v178
	v_exp_f32_e32 v82, v82
	v_bfe_i32 v216, v212, 2, 1
	v_and_b32_e32 v81, v81, v215
	v_fma_f32 v83, v83, s95, -v178
	v_exp_f32_e32 v83, v83
	v_bfe_i32 v217, v212, 3, 1
	v_and_b32_e32 v82, v82, v216
	v_fma_f32 v84, v84, s95, -v178
	v_exp_f32_e32 v84, v84
	v_bfe_i32 v218, v212, 8, 1
	v_and_b32_e32 v83, v83, v217
	v_fma_f32 v85, v85, s95, -v178
	v_exp_f32_e32 v85, v85
	v_bfe_i32 v219, v212, 9, 1
	v_and_b32_e32 v84, v84, v218
	v_fma_f32 v86, v86, s95, -v178
	v_exp_f32_e32 v86, v86
	v_bfe_i32 v214, v212, 10, 1
	v_and_b32_e32 v85, v85, v219
	v_fma_f32 v87, v87, s95, -v178
	v_exp_f32_e32 v87, v87
	v_bfe_i32 v215, v212, 11, 1
	v_and_b32_e32 v86, v86, v214
	v_fma_f32 v88, v88, s95, -v178
	v_exp_f32_e32 v88, v88
	v_bfe_i32 v216, v212, 16, 1
	v_and_b32_e32 v87, v87, v215
	v_fma_f32 v89, v89, s95, -v178
	v_exp_f32_e32 v89, v89
	v_bfe_i32 v217, v212, 17, 1
	v_and_b32_e32 v88, v88, v216
	v_fma_f32 v90, v90, s95, -v178
	v_exp_f32_e32 v90, v90
	v_bfe_i32 v218, v212, 18, 1
	v_and_b32_e32 v89, v89, v217
	v_fma_f32 v91, v91, s95, -v178
	v_exp_f32_e32 v91, v91
	v_bfe_i32 v219, v212, 19, 1
	v_and_b32_e32 v90, v90, v218
	v_fma_f32 v92, v92, s95, -v178
	v_exp_f32_e32 v92, v92
	v_bfe_i32 v214, v212, 24, 1
; #define LAS __attribute__((address_space(3)))
; DI unsigned pk2(float lo, float hi) { f32x2 v = {lo, hi}; bf16x2_t b = __builtin_convertvector(v, bf16x2_t); return __builtin_bit_cast(unsigned, b); }
; template <bool MASK>
; DI void attn_unit(LAS unsigned char* lds, const bf16_t* qrow, const bf16_t* kbase, int kpitch, const bf16_t* vtbase, int vtpitch, int ntiles,
;                   const unsigned long long* maskp, bf16_t* orow, float c1, float c2) {
;     ...
;         for (int sub = 0; sub < 2; ++sub) {
;             const unsigned mws = ((unsigned)(mw >> (32 * sub))) >> (4 * h);
;             float pe[16];
; #pragma unroll
;             for (int i = 0; i < 16; ++i) {
;                 float p = __builtin_amdgcn_exp2f(xs[sub][i] * c1 - c2);
;                 if (MASK) { const int m = __builtin_amdgcn_sbfe((int)mws, (i & 3) + 8 * (i >> 2), 1); p = __uint_as_float(__float_as_uint(p) & (unsigned)m); }
;                 l += p; pe[i] = p;
;             }
;             u32x4 p0, p1;
;             p0.x = pk2(pe[0], pe[1]); p0.y = pk2(pe[2], pe[3]); p0.z = pk2(pe[4], pe[5]); p0.w = pk2(pe[6], pe[7]);
;             p1.x = pk2(pe[8], pe[9]); p1.y = pk2(pe[10], pe[11]); p1.z = pk2(pe[12], pe[13]); p1.w = pk2(pe[14], pe[15]);
;             const bf16x8 pb0 = __builtin_bit_cast(bf16x8, p0), pb1 = __builtin_bit_cast(bf16x8, p1);
; #pragma unroll
;             for (int dt = 0; dt < 4; ++dt) {
;                 const LAS unsigned char* vp = buf + AK_BYTES + (32 * dt + r) * AV_PITCH + (32 * sub + 4 * h) * 2;
;                 const s16x4 lo0 = *(const LAS s16x4*)(vp), hi0 = *(const LAS s16x4*)(vp + 16);
;                 const s16x4 lo1 = *(const LAS s16x4*)(vp + 32), hi1 = *(const LAS s16x4*)(vp + 48);
;                 const bf16x8 va0 = __builtin_shufflevector(lo0, hi0, 0, 1, 2, 3, 4, 5, 6, 7);
;                 const bf16x8 va1 = __builtin_shufflevector(lo1, hi1, 0, 1, 2, 3, 4, 5, 6, 7);
;                 o[dt] = __builtin_amdgcn_mfma_f32_32x32x16_bf16(va0, pb0, o[dt], 0, 0, 0);
;                 o[dt] = __builtin_amdgcn_mfma_f32_32x32x16_bf16(va1, pb1, o[dt], 0, 0, 0);
;             }
	v_and_b32_e32 v91, v91, v219
	v_fma_f32 v93, v93, s95, -v178
	v_exp_f32_e32 v93, v93
	v_bfe_i32 v215, v212, 25, 1
	v_and_b32_e32 v92, v92, v214
	v_fma_f32 v94, v94, s95, -v178
	v_exp_f32_e32 v94, v94
	v_bfe_i32 v216, v212, 26, 1
	v_and_b32_e32 v93, v93, v215
	v_fma_f32 v95, v95, s95, -v178
	v_exp_f32_e32 v95, v95
	v_bfe_i32 v217, v212, 27, 1
	v_and_b32_e32 v94, v94, v216
	v_nop
	v_and_b32_e32 v95, v95, v217
	v_cvt_pk_bf16_f32 v182, v80, v81
	v_cvt_pk_bf16_f32 v183, v82, v83
	v_cvt_pk_bf16_f32 v184, v84, v85
	v_cvt_pk_bf16_f32 v185, v86, v87
	v_cvt_pk_bf16_f32 v200, v88, v89
	v_cvt_pk_bf16_f32 v201, v90, v91
	v_cvt_pk_bf16_f32 v202, v92, v93
	v_cvt_pk_bf16_f32 v203, v94, v95
	v_pk_add_f32 v[80:81], v[80:81], v[82:83]
	v_pk_add_f32 v[84:85], v[84:85], v[86:87]
	v_pk_add_f32 v[88:89], v[88:89], v[90:91]
	v_pk_add_f32 v[92:93], v[92:93], v[94:95]
	v_pk_add_f32 v[80:81], v[80:81], v[84:85]
	v_pk_add_f32 v[88:89], v[88:89], v[92:93]
	v_pk_add_f32 v[80:81], v[80:81], v[88:89]
	v_add_f32_e32 v80, v80, v81
	v_add_f32_e32 v149, v149, v80
	v_fma_f32 v64, v64, s95, -v178
	v_exp_f32_e32 v64, v64
	v_bfe_i32 v214, v213, 0, 1
	v_fma_f32 v65, v65, s95, -v178
	v_exp_f32_e32 v65, v65
	v_bfe_i32 v215, v213, 1, 1
	v_and_b32_e32 v64, v64, v214
	v_fma_f32 v66, v66, s95, -v178
	v_exp_f32_e32 v66, v66
	v_bfe_i32 v216, v213, 2, 1
	v_and_b32_e32 v65, v65, v215
	v_fma_f32 v67, v67, s95, -v178
	v_exp_f32_e32 v67, v67
	v_bfe_i32 v217, v213, 3, 1
	v_and_b32_e32 v66, v66, v216
	v_fma_f32 v68, v68, s95, -v178
	v_exp_f32_e32 v68, v68
	v_bfe_i32 v218, v213, 8, 1
	v_and_b32_e32 v67, v67, v217
	v_fma_f32 v69, v69, s95, -v178
	v_exp_f32_e32 v69, v69
	v_bfe_i32 v219, v213, 9, 1
	v_and_b32_e32 v68, v68, v218
	v_fma_f32 v70, v70, s95, -v178
	v_exp_f32_e32 v70, v70
	v_bfe_i32 v214, v213, 10, 1
	v_and_b32_e32 v69, v69, v219
	v_fma_f32 v71, v71, s95, -v178
	v_exp_f32_e32 v71, v71
	v_bfe_i32 v215, v213, 11, 1
	v_and_b32_e32 v70, v70, v214
	v_fma_f32 v72, v72, s95, -v178
	v_exp_f32_e32 v72, v72
	v_bfe_i32 v216, v213, 16, 1
	v_and_b32_e32 v71, v71, v215
	v_fma_f32 v73, v73, s95, -v178
	v_exp_f32_e32 v73, v73
	v_bfe_i32 v217, v213, 17, 1
	v_and_b32_e32 v72, v72, v216
	v_fma_f32 v74, v74, s95, -v178
	v_exp_f32_e32 v74, v74
	v_bfe_i32 v218, v213, 18, 1
	v_and_b32_e32 v73, v73, v217
	v_fma_f32 v75, v75, s95, -v178
	v_exp_f32_e32 v75, v75
	v_bfe_i32 v219, v213, 19, 1
	v_and_b32_e32 v74, v74, v218
	v_fma_f32 v76, v76, s95, -v178
	v_exp_f32_e32 v76, v76
	v_bfe_i32 v214, v213, 24, 1
	v_and_b32_e32 v75, v75, v219
	v_fma_f32 v77, v77, s95, -v178
	v_exp_f32_e32 v77, v77
	v_bfe_i32 v215, v213, 25, 1
	v_and_b32_e32 v76, v76, v214
	v_fma_f32 v78, v78, s95, -v178
	v_exp_f32_e32 v78, v78
	v_bfe_i32 v216, v213, 26, 1
	v_and_b32_e32 v77, v77, v215
	v_fma_f32 v79, v79, s95, -v178
	v_exp_f32_e32 v79, v79
	v_bfe_i32 v217, v213, 27, 1
	v_and_b32_e32 v78, v78, v216
	v_nop
	v_and_b32_e32 v79, v79, v217
	v_cvt_pk_bf16_f32 v204, v64, v65
	v_cvt_pk_bf16_f32 v205, v66, v67
	v_cvt_pk_bf16_f32 v206, v68, v69
	v_cvt_pk_bf16_f32 v207, v70, v71
	v_cvt_pk_bf16_f32 v208, v72, v73
	v_cvt_pk_bf16_f32 v209, v74, v75
	v_cvt_pk_bf16_f32 v210, v76, v77
	v_cvt_pk_bf16_f32 v211, v78, v79
	v_pk_add_f32 v[64:65], v[64:65], v[66:67]
	v_pk_add_f32 v[68:69], v[68:69], v[70:71]
	v_pk_add_f32 v[72:73], v[72:73], v[74:75]
	v_pk_add_f32 v[76:77], v[76:77], v[78:79]
	v_pk_add_f32 v[64:65], v[64:65], v[68:69]
	v_pk_add_f32 v[72:73], v[72:73], v[76:77]
	v_pk_add_f32 v[64:65], v[64:65], v[72:73]
	v_add_f32_e32 v64, v64, v65
	v_add_f32_e32 v149, v149, v64
	s_cmp_lt_i32 s18, s17
	s_cbranch_scc0 .Lat_b_last
	v_add3_u32 v167, s24, v151, v180
	v_add_u32_e32 v168, 0x5000, v167
	v_add_u32_e32 v169, 0x6000, v167
	v_add_u32_e32 v199, 0x7000, v167
	v_add_u32_e32 v167, 0x4000, v167
	v_add3_u32 v166, s21, v160, v153
	ds_read2_b64 v[212:215], v167 offset0:128 offset1:130
	ds_read2_b64 v[216:219], v167 offset0:132 offset1:134
	ds_read2_b64 v[220:223], v168 offset0:160 offset1:162
	ds_read2_b64 v[224:227], v168 offset0:164 offset1:166
	ds_read2_b64 v[228:231], v169 offset0:192 offset1:194
	ds_read2_b64 v[232:235], v169 offset0:196 offset1:198
	ds_read2_b64 v[236:239], v199 offset0:224 offset1:226
	ds_read2_b64 v[240:243], v199 offset0:228 offset1:230
	ds_read2_b64 v[244:247], v167 offset0:136 offset1:138
	ds_read2_b64 v[248:251], v167 offset0:140 offset1:142
	s_waitcnt lgkmcnt(9)
	v_mfma_f32_32x32x16_bf16 v[48:63], v[212:215], v[182:185], v[48:63]
	ds_read2_b64 v[212:215], v168 offset0:168 offset1:170
	s_waitcnt lgkmcnt(9)
	v_mfma_f32_32x32x16_bf16 v[48:63], v[216:219], v[200:203], v[48:63]
	ds_read2_b64 v[216:219], v168 offset0:172 offset1:174
	s_waitcnt lgkmcnt(9)
	v_mfma_f32_32x32x16_bf16 v[32:47], v[220:223], v[182:185], v[32:47]
	ds_read2_b64 v[220:223], v169 offset0:200 offset1:202
	s_waitcnt lgkmcnt(9)
	v_mfma_f32_32x32x16_bf16 v[32:47], v[224:227], v[200:203], v[32:47]
	ds_read2_b64 v[224:227], v169 offset0:204 offset1:206
	s_waitcnt lgkmcnt(9)
	v_mfma_f32_32x32x16_bf16 v[16:31], v[228:231], v[182:185], v[16:31]
	ds_read2_b64 v[228:231], v199 offset0:232 offset1:234
	s_waitcnt lgkmcnt(9)
	v_mfma_f32_32x32x16_bf16 v[16:31], v[232:235], v[200:203], v[16:31]
	ds_read2_b64 v[232:235], v199 offset0:236 offset1:238
	s_waitcnt lgkmcnt(9)
	v_mfma_f32_32x32x16_bf16 v[0:15], v[236:239], v[182:185], v[0:15]
	ds_read_b128 v[236:239], v166
	s_waitcnt lgkmcnt(9)
	v_mfma_f32_32x32x16_bf16 v[0:15], v[240:243], v[200:203], v[0:15]
	ds_read_b128 v[240:243], v166 offset:32
	s_waitcnt lgkmcnt(9)
	v_mfma_f32_32x32x16_bf16 v[48:63], v[244:247], v[204:207], v[48:63]
	ds_read_b128 v[244:247], v166 offset:64
	s_waitcnt lgkmcnt(9)
; #define LAS __attribute__((address_space(3)))
; template <bool MASK>
; DI void attn_unit(LAS unsigned char* lds, const bf16_t* qrow, const bf16_t* kbase, int kpitch, const bf16_t* vtbase, int vtpitch, int ntiles,
;                   const unsigned long long* maskp, bf16_t* orow, float c1, float c2) {
;     ...
; #pragma unroll
;         for (int sub = 0; sub < 2; ++sub) {
; #pragma unroll
;             for (int i = 0; i < 16; ++i) xs[sub][i] = 0.f;
;             __builtin_amdgcn_s_setprio(1);
; #pragma unroll
;             for (int ks = 0; ks < 8; ++ks) {
;                 const bf16x8 a = *(const LAS bf16x8*)(buf + (32 * sub + r) * AK_PITCH + ks * 32 + h * 16);
;                 xs[sub] = __builtin_amdgcn_mfma_f32_32x32x16_bf16(a, qf[ks], xs[sub], 0, 0, 0);
;             }
;             __builtin_amdgcn_s_setprio(0);
;         }
	v_mfma_f32_32x32x16_bf16 v[48:63], v[248:251], v[208:211], v[48:63]
	ds_read_b128 v[248:251], v166 offset:96
	s_waitcnt lgkmcnt(9)
	v_mfma_f32_32x32x16_bf16 v[32:47], v[212:215], v[204:207], v[32:47]
	ds_read_b128 v[212:215], v166 offset:128
	s_waitcnt lgkmcnt(9)
	v_mfma_f32_32x32x16_bf16 v[32:47], v[216:219], v[208:211], v[32:47]
	ds_read_b128 v[216:219], v166 offset:160
	s_waitcnt lgkmcnt(9)
	v_mfma_f32_32x32x16_bf16 v[16:31], v[220:223], v[204:207], v[16:31]
	ds_read_b128 v[220:223], v166 offset:192
	s_waitcnt lgkmcnt(9)
	v_mfma_f32_32x32x16_bf16 v[16:31], v[224:227], v[208:211], v[16:31]
	ds_read_b128 v[224:227], v166 offset:224
	s_waitcnt lgkmcnt(9)
	v_mfma_f32_32x32x16_bf16 v[0:15], v[228:231], v[204:207], v[0:15]
	ds_read_b128 v[228:231], v166 offset:8704
	s_waitcnt lgkmcnt(9)
	v_mfma_f32_32x32x16_bf16 v[0:15], v[232:235], v[208:211], v[0:15]
	ds_read_b128 v[232:235], v166 offset:8736
	s_waitcnt lgkmcnt(9)
	v_mfma_f32_32x32x16_bf16 v[80:95], v[236:239], v[112:115], 0
	ds_read_b128 v[236:239], v166 offset:8768
	s_waitcnt lgkmcnt(9)
	v_mfma_f32_32x32x16_bf16 v[80:95], v[240:243], v[116:119], v[80:95]
	ds_read_b128 v[240:243], v166 offset:8800
	s_waitcnt lgkmcnt(9)
	v_mfma_f32_32x32x16_bf16 v[80:95], v[244:247], v[120:123], v[80:95]
	ds_read_b128 v[244:247], v166 offset:8832
	s_waitcnt lgkmcnt(9)
	v_mfma_f32_32x32x16_bf16 v[80:95], v[248:251], v[124:127], v[80:95]
	ds_read_b128 v[248:251], v166 offset:8864
	s_waitcnt lgkmcnt(9)
	v_mfma_f32_32x32x16_bf16 v[80:95], v[212:215], v[128:131], v[80:95]
	ds_read_b128 v[212:215], v166 offset:8896
	s_waitcnt lgkmcnt(9)
	v_mfma_f32_32x32x16_bf16 v[80:95], v[216:219], v[132:135], v[80:95]
	ds_read_b128 v[216:219], v166 offset:8928
	s_waitcnt lgkmcnt(9)
	v_mfma_f32_32x32x16_bf16 v[80:95], v[220:223], v[136:139], v[80:95]
	s_waitcnt lgkmcnt(8)
	v_mfma_f32_32x32x16_bf16 v[80:95], v[224:227], v[140:143], v[80:95]
	s_waitcnt lgkmcnt(7)
	v_mfma_f32_32x32x16_bf16 v[64:79], v[228:231], v[112:115], 0
	s_waitcnt lgkmcnt(6)
	v_mfma_f32_32x32x16_bf16 v[64:79], v[232:235], v[116:119], v[64:79]
	s_waitcnt lgkmcnt(5)
	v_mfma_f32_32x32x16_bf16 v[64:79], v[236:239], v[120:123], v[64:79]
	s_waitcnt lgkmcnt(4)
	v_mfma_f32_32x32x16_bf16 v[64:79], v[240:243], v[124:127], v[64:79]
	s_waitcnt lgkmcnt(3)
	v_mfma_f32_32x32x16_bf16 v[64:79], v[244:247], v[128:131], v[64:79]
	s_waitcnt lgkmcnt(2)
	v_mfma_f32_32x32x16_bf16 v[64:79], v[248:251], v[132:135], v[64:79]
	s_waitcnt lgkmcnt(1)
	v_mfma_f32_32x32x16_bf16 v[64:79], v[212:215], v[136:139], v[64:79]
	s_waitcnt lgkmcnt(0)
	v_mfma_f32_32x32x16_bf16 v[64:79], v[216:219], v[140:143], v[64:79]
	s_branch .Lat_bottom
; #define LAS __attribute__((address_space(3)))
; template <bool MASK>
; DI void attn_unit(LAS unsigned char* lds, const bf16_t* qrow, const bf16_t* kbase, int kpitch, const bf16_t* vtbase, int vtpitch, int ntiles,
;                   const unsigned long long* maskp, bf16_t* orow, float c1, float c2) {
;     ...
; #pragma unroll
;         for (int sub = 0; sub < 2; ++sub) {
; #pragma unroll
;             for (int i = 0; i < 16; ++i) xs[sub][i] = 0.f;
;             __builtin_amdgcn_s_setprio(1);
; #pragma unroll
;             for (int ks = 0; ks < 8; ++ks) {
;                 const bf16x8 a = *(const LAS bf16x8*)(buf + (32 * sub + r) * AK_PITCH + ks * 32 + h * 16);
;                 xs[sub] = __builtin_amdgcn_mfma_f32_32x32x16_bf16(a, qf[ks], xs[sub], 0, 0, 0);
;             }
;             __builtin_amdgcn_s_setprio(0);
;         }
; #pragma unroll
;         for (int sub = 0; sub < 2; ++sub) {
;             const unsigned mws = ((unsigned)(mw >> (32 * sub))) >> (4 * h);
;             float pe[16];
; #pragma unroll
;             for (int i = 0; i < 16; ++i) {
;                 float p = __builtin_amdgcn_exp2f(xs[sub][i] * c1 - c2);
;                 if (MASK) { const int m = __builtin_amdgcn_sbfe((int)mws, (i & 3) + 8 * (i >> 2), 1); p = __uint_as_float(__float_as_uint(p) & (unsigned)m); }
;                 l += p; pe[i] = p;
;             }
;             u32x4 p0, p1;
;             p0.x = pk2(pe[0], pe[1]); p0.y = pk2(pe[2], pe[3]); p0.z = pk2(pe[4], pe[5]); p0.w = pk2(pe[6], pe[7]);
;             p1.x = pk2(pe[8], pe[9]); p1.y = pk2(pe[10], pe[11]); p1.z = pk2(pe[12], pe[13]); p1.w = pk2(pe[14], pe[15]);
;             const bf16x8 pb0 = __builtin_bit_cast(bf16x8, p0), pb1 = __builtin_bit_cast(bf16x8, p1);
; #pragma unroll
;             for (int dt = 0; dt < 4; ++dt) {
;                 const LAS unsigned char* vp = buf + AK_BYTES + (32 * dt + r) * AV_PITCH + (32 * sub + 4 * h) * 2;
;                 const s16x4 lo0 = *(const LAS s16x4*)(vp), hi0 = *(const LAS s16x4*)(vp + 16);
;                 const s16x4 lo1 = *(const LAS s16x4*)(vp + 32), hi1 = *(const LAS s16x4*)(vp + 48);
;                 const bf16x8 va0 = __builtin_shufflevector(lo0, hi0, 0, 1, 2, 3, 4, 5, 6, 7);
;                 const bf16x8 va1 = __builtin_shufflevector(lo1, hi1, 0, 1, 2, 3, 4, 5, 6, 7);
;                 o[dt] = __builtin_amdgcn_mfma_f32_32x32x16_bf16(va0, pb0, o[dt], 0, 0, 0);
.Lat_b_first:
	v_add3_u32 v166, s21, v160, v153
	ds_read_b128 v[212:215], v166
	ds_read_b128 v[216:219], v166 offset:32
	ds_read_b128 v[220:223], v166 offset:64
	ds_read_b128 v[224:227], v166 offset:96
	ds_read_b128 v[228:231], v166 offset:128
	ds_read_b128 v[232:235], v166 offset:160
	ds_read_b128 v[236:239], v166 offset:192
	ds_read_b128 v[240:243], v166 offset:224
	ds_read_b128 v[244:247], v166 offset:8704
	ds_read_b128 v[248:251], v166 offset:8736
	s_waitcnt lgkmcnt(9)
	v_mfma_f32_32x32x16_bf16 v[80:95], v[212:215], v[112:115], 0
	ds_read_b128 v[212:215], v166 offset:8768
	s_waitcnt lgkmcnt(9)
	v_mfma_f32_32x32x16_bf16 v[80:95], v[216:219], v[116:119], v[80:95]
	ds_read_b128 v[216:219], v166 offset:8800
	s_waitcnt lgkmcnt(9)
	v_mfma_f32_32x32x16_bf16 v[80:95], v[220:223], v[120:123], v[80:95]
	ds_read_b128 v[220:223], v166 offset:8832
	s_waitcnt lgkmcnt(9)
	v_mfma_f32_32x32x16_bf16 v[80:95], v[224:227], v[124:127], v[80:95]
	ds_read_b128 v[224:227], v166 offset:8864
	s_waitcnt lgkmcnt(9)
	v_mfma_f32_32x32x16_bf16 v[80:95], v[228:231], v[128:131], v[80:95]
	ds_read_b128 v[228:231], v166 offset:8896
	s_waitcnt lgkmcnt(9)
	v_mfma_f32_32x32x16_bf16 v[80:95], v[232:235], v[132:135], v[80:95]
	ds_read_b128 v[232:235], v166 offset:8928
	s_waitcnt lgkmcnt(9)
	v_mfma_f32_32x32x16_bf16 v[80:95], v[236:239], v[136:139], v[80:95]
	s_waitcnt lgkmcnt(8)
	v_mfma_f32_32x32x16_bf16 v[80:95], v[240:243], v[140:143], v[80:95]
	s_waitcnt lgkmcnt(7)
	v_mfma_f32_32x32x16_bf16 v[64:79], v[244:247], v[112:115], 0
	s_waitcnt lgkmcnt(6)
	v_mfma_f32_32x32x16_bf16 v[64:79], v[248:251], v[116:119], v[64:79]
	s_waitcnt lgkmcnt(5)
	v_mfma_f32_32x32x16_bf16 v[64:79], v[212:215], v[120:123], v[64:79]
	s_waitcnt lgkmcnt(4)
	v_mfma_f32_32x32x16_bf16 v[64:79], v[216:219], v[124:127], v[64:79]
	s_waitcnt lgkmcnt(3)
	v_mfma_f32_32x32x16_bf16 v[64:79], v[220:223], v[128:131], v[64:79]
	s_waitcnt lgkmcnt(2)
	v_mfma_f32_32x32x16_bf16 v[64:79], v[224:227], v[132:135], v[64:79]
	s_waitcnt lgkmcnt(1)
	v_mfma_f32_32x32x16_bf16 v[64:79], v[228:231], v[136:139], v[64:79]
	s_waitcnt lgkmcnt(0)
	v_mfma_f32_32x32x16_bf16 v[64:79], v[232:235], v[140:143], v[64:79]
	s_branch .Lat_bottom
.Lat_b_last:
	v_add3_u32 v167, s24, v151, v180
	v_add_u32_e32 v168, 0x5000, v167
	v_add_u32_e32 v169, 0x6000, v167
	v_add_u32_e32 v199, 0x7000, v167
	v_add_u32_e32 v167, 0x4000, v167
	ds_read2_b64 v[212:215], v167 offset0:128 offset1:130
	ds_read2_b64 v[216:219], v167 offset0:132 offset1:134
	ds_read2_b64 v[220:223], v168 offset0:160 offset1:162
	ds_read2_b64 v[224:227], v168 offset0:164 offset1:166
	ds_read2_b64 v[228:231], v169 offset0:192 offset1:194
	ds_read2_b64 v[232:235], v169 offset0:196 offset1:198
	ds_read2_b64 v[236:239], v199 offset0:224 offset1:226
	ds_read2_b64 v[240:243], v199 offset0:228 offset1:230
	ds_read2_b64 v[244:247], v167 offset0:136 offset1:138
	ds_read2_b64 v[248:251], v167 offset0:140 offset1:142
	s_waitcnt lgkmcnt(9)
	v_mfma_f32_32x32x16_bf16 v[48:63], v[212:215], v[182:185], v[48:63]
	ds_read2_b64 v[212:215], v168 offset0:168 offset1:170
	s_waitcnt lgkmcnt(9)
	v_mfma_f32_32x32x16_bf16 v[48:63], v[216:219], v[200:203], v[48:63]
	ds_read2_b64 v[216:219], v168 offset0:172 offset1:174
	s_waitcnt lgkmcnt(9)
	v_mfma_f32_32x32x16_bf16 v[32:47], v[220:223], v[182:185], v[32:47]
	ds_read2_b64 v[220:223], v169 offset0:200 offset1:202
	s_waitcnt lgkmcnt(9)
	v_mfma_f32_32x32x16_bf16 v[32:47], v[224:227], v[200:203], v[32:47]
	ds_read2_b64 v[224:227], v169 offset0:204 offset1:206
	s_waitcnt lgkmcnt(9)
	v_mfma_f32_32x32x16_bf16 v[16:31], v[228:231], v[182:185], v[16:31]
	ds_read2_b64 v[228:231], v199 offset0:232 offset1:234
	s_waitcnt lgkmcnt(9)
	v_mfma_f32_32x32x16_bf16 v[16:31], v[232:235], v[200:203], v[16:31]
	ds_read2_b64 v[232:235], v199 offset0:236 offset1:238
	s_waitcnt lgkmcnt(9)
	v_mfma_f32_32x32x16_bf16 v[0:15], v[236:239], v[182:185], v[0:15]
	s_waitcnt lgkmcnt(8)
	v_mfma_f32_32x32x16_bf16 v[0:15], v[240:243], v[200:203], v[0:15]
	s_waitcnt lgkmcnt(7)
	v_mfma_f32_32x32x16_bf16 v[48:63], v[244:247], v[204:207], v[48:63]
	s_waitcnt lgkmcnt(6)
	v_mfma_f32_32x32x16_bf16 v[48:63], v[248:251], v[208:211], v[48:63]
	s_waitcnt lgkmcnt(5)
	v_mfma_f32_32x32x16_bf16 v[32:47], v[212:215], v[204:207], v[32:47]
	s_waitcnt lgkmcnt(4)
	v_mfma_f32_32x32x16_bf16 v[32:47], v[216:219], v[208:211], v[32:47]
	s_waitcnt lgkmcnt(3)
	v_mfma_f32_32x32x16_bf16 v[16:31], v[220:223], v[204:207], v[16:31]
	s_waitcnt lgkmcnt(2)
	v_mfma_f32_32x32x16_bf16 v[16:31], v[224:227], v[208:211], v[16:31]
	s_waitcnt lgkmcnt(1)
	v_mfma_f32_32x32x16_bf16 v[0:15], v[228:231], v[204:207], v[0:15]
	s_waitcnt lgkmcnt(0)
	v_mfma_f32_32x32x16_bf16 v[0:15], v[232:235], v[208:211], v[0:15]

; #define LAS __attribute__((address_space(3)))
; template <bool MASK>
; DI void attn_unit(LAS unsigned char* lds, const bf16_t* qrow, const bf16_t* kbase, int kpitch, const bf16_t* vtbase, int vtpitch, int ntiles,
;                   const unsigned long long* maskp, bf16_t* orow, float c1, float c2) {
;     ...
;         if (more) {
;             LAS unsigned char* nb = lds + ((kt + 1) & 1) * ABUF;
;             *(LAS u32x4*)(nb + kl0) = pk[0]; *(LAS u32x4*)(nb + kl1) = pk[1];
;             *(LAS u32x2*)(nb + vl0) = (u32x2){pv[0].x, pv[0].y}; *(LAS u32x2*)(nb + vl0 + 8) = (u32x2){pv[0].z, pv[0].w};
;             *(LAS u32x2*)(nb + vl1) = (u32x2){pv[1].x, pv[1].y}; *(LAS u32x2*)(nb + vl1 + 8) = (u32x2){pv[1].z, pv[1].w};
;         }
;         __syncthreads();
;     }
.Lat_nowrite:
	s_waitcnt vmcnt(0)
	v_mov_b64_e32 v[176:177], v[174:175]
	s_mov_b32 s2, s24
	s_mov_b32 s24, s21
	s_mov_b32 s21, s23
	s_mov_b32 s23, s2
	s_add_i32 s18, s18, 1
	s_cmp_le_i32 s18, s17
	s_waitcnt lgkmcnt(0)
	s_barrier
	s_cbranch_scc1 .Lat_top
	s_nop 0
	s_nop 0
	s_nop 0
	s_nop 0
	s_nop 0
	s_nop 0
	s_nop 0
	s_nop 0
	s_nop 0
	s_nop 0
	s_nop 0
	s_nop 0
	s_nop 0
	s_nop 0
	s_nop 0
	v_mov_b32_e32 v64, v147
	s_branch .LBB0_1238
